# final-norm tail: row-sum slots polled directly (sentinel-initialised at seam 2) instead of arrival counter + second round trip; final-norm gain loads hoisted above the poll
# speedup vs baseline: 1.0130x; 1.0013x over previous
; #define LAS __attribute__((address_space(3)))
; #define TR_LOAD(p) __builtin_nontemporal_load(p)
; __device__ __forceinline__ TrItem tr_decode(int it, const float* const* in, unsigned char* ws, int lane) {
;     ...
;     const int rh = r >> 3, rl = r & 7, nq = ndb >> DL, kbh = rh / nq, dbh = rh - kbh * nq;
;     const int kb = (kbh << KL) + (rl >> DL), db = (dbh << DL) + (rl & ((1 << DL) - 1)), d0 = db * 64, k0 = kb * 64;
;     ...
;     const int kb = r / ndb, db = r - kb * ndb, d0 = db * 64, k0 = kb * 64;
;     ...
;     const int blk = d0 + 32 * ((lane & 15) >> 3);
;     const float* src = W; int s0 = blk;
;     if (kind == 1) { const int pn = blk >> 8, bj = (blk >> 7) & 1, o = blk & 127; src = bj ? W2 : W; s0 = pn * 128 + o; }
;     else if (kind == 2) s0 = win_src(blk);
;     TrItem t; t.src = src + (size_t)(k0 + (lane >> 4)) * N + s0 + 4 * (lane & 7); t.gain = gain ? gain + k0 + 8 * (lane & 7) : nullptr;
;     t.dst = WT + (size_t)(d0 + (lane >> 3)) * K + k0 + 8 * (lane & 7); t.N = N; t.K = K; t.nts = nts && TR_NTS;
; __device__ __forceinline__ void tr_all(const float* const* in, unsigned char* ws, LAS float* scr, int gw, int ngw, int lane, const TrRanges rg) {
;     ...
;     for (int i = 0; i < 16; ++i) v[i] = TR_LOAD((const f32x4*)(cur.src + (size_t)(4 * i) * cur.N));
;     for (int it = gw; it < TR_CNT; it += ngw) {
;         const int nit = it + ngw; const bool hn = nit < TR_CNT;
;         TrItem nx = cur; f32x4 w[16];
;         if (hn) { nx = tr_decode(rg.item(nit), in, ws, lane);
; #pragma unroll
;             for (int i = 0; i < 16; ++i) w[i] = TR_LOAD((const f32x4*)(nx.src + (size_t)(4 * i) * nx.N)); }
;         LAS float* wp = scr + (lane >> 4) * 65 + 4 * (lane & 15);
; #pragma unroll
;         for (int i = 0; i < 16; ++i) { wp[(4 * i) * 65 + 0] = v[i][0]; wp[(4 * i) * 65 + 1] = v[i][1]; wp[(4 * i) * 65 + 2] = v[i][2]; wp[(4 * i) * 65 + 3] = v[i][3]; }
;         f32x4 g0 = {1.f, 1.f, 1.f, 1.f}, g1 = {1.f, 1.f, 1.f, 1.f};
;         if (cur.gain) { g0 = *(const f32x4*)cur.gain; g1 = *(const f32x4*)(cur.gain + 4); }
.Lseam_cv_2:
	s_cmp_lt_u32 s98, 2
	s_cbranch_scc1 .LBB0_681
	s_cmp_gt_u32 s98, 5
	s_cbranch_scc1 .Lseam_cv_2_1
	s_mov_b64 exec, -1
	s_lshl_b32 s99, s87, 2
	s_add_i32 s99, s99, s98
	s_add_i32 s99, s99, 0xdfe
	s_lshr_b32 s100, s99, 3
	s_mul_i32 s101, s100, 0x5d2
	s_lshr_b32 s101, s101, 16
	s_mul_i32 vcc_lo, s101, 44
	s_sub_i32 s100, s100, vcc_lo
	s_and_b32 vcc_lo, s99, 7
	s_lshr_b32 vcc_hi, vcc_lo, 2
	s_lshl_b32 s101, s101, 1
	s_add_i32 s101, s101, vcc_hi
	s_and_b32 vcc_lo, vcc_lo, 3
	s_lshl_b32 s100, s100, 2
	s_add_i32 s100, s100, vcc_lo
	s_lshl_b32 s101, s101, 6
	s_lshl_b32 s100, s100, 6
	v_and_b32_e32 v66, 63, v1
	v_lshrrev_b32_e32 v67, 4, v66
	v_and_b32_e32 v68, 15, v66
	v_and_b32_e32 v73, 7, v66
	v_lshrrev_b32_e32 v72, 3, v66
	s_mul_i32 s99, s98, 0x4100
	v_mul_u32_u24_e32 v70, 0x104, v67
	v_lshl_add_u32 v70, v68, 4, v70
	v_add_u32_e32 v70, s99, v70
	v_mul_u32_u24_e32 v71, 0x820, v73
	v_lshl_add_u32 v71, v72, 2, v71
	v_add_u32_e32 v71, s99, v71
	s_mul_i32 s99, s101, 0x1600
	s_lshr_b32 vcc_lo, s100, 8
	s_lshl_b32 vcc_lo, vcc_lo, 7
	s_add_i32 s99, s99, vcc_lo
	s_and_b32 vcc_lo, s100, 0x7f
	s_add_i32 s99, s99, vcc_lo
	s_lshl_b32 s99, s99, 2
	v_mul_u32_u24_e32 v69, 0x5800, v67
	v_lshl_add_u32 v69, v68, 4, v69
	v_add_u32_e32 v69, s99, v69
	s_lshl_b32 s99, s100, 12
	s_lshl_b32 vcc_lo, s101, 1
	s_add_i32 s99, s99, vcc_lo
	v_lshlrev_b32_e32 v72, 12, v72
	v_lshl_add_u32 v72, v73, 4, v72
	v_add_u32_e32 v72, s99, v72
	s_lshl_b32 s99, s101, 2
	v_lshlrev_b32_e32 v73, 5, v73
	v_add_u32_e32 v73, s99, v73
	s_nop 0
	s_bitcmp1_b32 s100, 7
	v_readlane_b32 s100, v254, 6
	v_readlane_b32 s101, v254, 7
	v_readlane_b32 s98, v254, 8
	v_readlane_b32 s99, v254, 9
	s_nop 3
	s_cselect_b32 s100, s98, s100
	s_cselect_b32 s101, s99, s101
	v_readlane_b32 s98, v254, 4
	v_readlane_b32 s99, v254, 5
	global_load_dwordx4 v[2:5], v69, s[100:101] nt
	v_add_u32_e32 v68, 0x16000, v69
	global_load_dwordx4 v[6:9], v68, s[100:101] nt
	v_add_u32_e32 v67, 0x2c000, v69
	global_load_dwordx4 v[10:13], v67, s[100:101] nt
	v_add_u32_e32 v68, 0x42000, v69
	global_load_dwordx4 v[14:17], v68, s[100:101] nt
	v_add_u32_e32 v67, 0x58000, v69
	global_load_dwordx4 v[18:21], v67, s[100:101] nt
	v_add_u32_e32 v68, 0x6e000, v69
	global_load_dwordx4 v[22:25], v68, s[100:101] nt
	v_add_u32_e32 v67, 0x84000, v69
	global_load_dwordx4 v[26:29], v67, s[100:101] nt
	v_add_u32_e32 v68, 0x9a000, v69
	global_load_dwordx4 v[30:33], v68, s[100:101] nt
	v_add_u32_e32 v67, 0xb0000, v69
	global_load_dwordx4 v[34:37], v67, s[100:101] nt
	v_add_u32_e32 v68, 0xc6000, v69
	global_load_dwordx4 v[38:41], v68, s[100:101] nt
	v_add_u32_e32 v67, 0xdc000, v69
	global_load_dwordx4 v[42:45], v67, s[100:101] nt
	v_add_u32_e32 v68, 0xf2000, v69
	global_load_dwordx4 v[46:49], v68, s[100:101] nt
	v_add_u32_e32 v67, 0x108000, v69
	global_load_dwordx4 v[50:53], v67, s[100:101] nt
	v_add_u32_e32 v68, 0x11e000, v69
	global_load_dwordx4 v[54:57], v68, s[100:101] nt
	v_add_u32_e32 v67, 0x134000, v69
	global_load_dwordx4 v[58:61], v67, s[100:101] nt
	v_add_u32_e32 v68, 0x14a000, v69
	global_load_dwordx4 v[62:65], v68, s[100:101] nt
	global_load_dwordx4 v[74:77], v73, s[98:99]
	global_load_dwordx4 v[78:81], v73, s[98:99] offset:16
	s_waitcnt vmcnt(17)
	ds_write_b32 v70, v2
	ds_write_b32 v70, v3 offset:4
	ds_write_b32 v70, v4 offset:8
	ds_write_b32 v70, v5 offset:12
	s_waitcnt vmcnt(16)
	ds_write_b32 v70, v6 offset:1040
	ds_write_b32 v70, v7 offset:1044
	ds_write_b32 v70, v8 offset:1048
	ds_write_b32 v70, v9 offset:1052
	s_waitcnt vmcnt(15)
	ds_write_b32 v70, v10 offset:2080
	ds_write_b32 v70, v11 offset:2084
	ds_write_b32 v70, v12 offset:2088
	ds_write_b32 v70, v13 offset:2092
	s_waitcnt vmcnt(14)
	ds_write_b32 v70, v14 offset:3120
	ds_write_b32 v70, v15 offset:3124
	ds_write_b32 v70, v16 offset:3128
	ds_write_b32 v70, v17 offset:3132
	s_waitcnt vmcnt(13)
	ds_write_b32 v70, v18 offset:4160
	ds_write_b32 v70, v19 offset:4164
	ds_write_b32 v70, v20 offset:4168
	ds_write_b32 v70, v21 offset:4172
	s_waitcnt vmcnt(12)
	ds_write_b32 v70, v22 offset:5200
	ds_write_b32 v70, v23 offset:5204
	ds_write_b32 v70, v24 offset:5208
	ds_write_b32 v70, v25 offset:5212
	s_waitcnt vmcnt(11)
	ds_write_b32 v70, v26 offset:6240
	ds_write_b32 v70, v27 offset:6244
	ds_write_b32 v70, v28 offset:6248
	ds_write_b32 v70, v29 offset:6252
	s_waitcnt vmcnt(10)
	ds_write_b32 v70, v30 offset:7280
	ds_write_b32 v70, v31 offset:7284
	ds_write_b32 v70, v32 offset:7288
	ds_write_b32 v70, v33 offset:7292
	s_waitcnt vmcnt(9)
	ds_write_b32 v70, v34 offset:8320
	ds_write_b32 v70, v35 offset:8324
	ds_write_b32 v70, v36 offset:8328
	ds_write_b32 v70, v37 offset:8332
	s_waitcnt vmcnt(8)
	ds_write_b32 v70, v38 offset:9360
	ds_write_b32 v70, v39 offset:9364
	ds_write_b32 v70, v40 offset:9368
	ds_write_b32 v70, v41 offset:9372
	s_waitcnt vmcnt(7)
	ds_write_b32 v70, v42 offset:10400
	ds_write_b32 v70, v43 offset:10404
	ds_write_b32 v70, v44 offset:10408
	ds_write_b32 v70, v45 offset:10412
	s_waitcnt vmcnt(6)
	ds_write_b32 v70, v46 offset:11440
	ds_write_b32 v70, v47 offset:11444
	ds_write_b32 v70, v48 offset:11448
	ds_write_b32 v70, v49 offset:11452
	s_waitcnt vmcnt(5)
	ds_write_b32 v70, v50 offset:12480
	ds_write_b32 v70, v51 offset:12484
	ds_write_b32 v70, v52 offset:12488
	ds_write_b32 v70, v53 offset:12492
	s_waitcnt vmcnt(4)
	ds_write_b32 v70, v54 offset:13520
	ds_write_b32 v70, v55 offset:13524
	ds_write_b32 v70, v56 offset:13528
	ds_write_b32 v70, v57 offset:13532
	s_waitcnt vmcnt(3)
	ds_write_b32 v70, v58 offset:14560
	ds_write_b32 v70, v59 offset:14564
	ds_write_b32 v70, v60 offset:14568
	ds_write_b32 v70, v61 offset:14572
	s_waitcnt vmcnt(2)
; #define LAS __attribute__((address_space(3)))
; __device__ __forceinline__ unsigned cvtpk(float lo, float hi) { f32x2_t v = {lo, hi}; bf16x2_t b = __builtin_convertvector(v, bf16x2_t); return __builtin_bit_cast(unsigned, b); }
;     __device__ __forceinline__ void fused(f32x4 (&acc)[2][2][4][2], const Unit& u, int wr, int wc, int fr, int fq, PG8_LAS unsigned char* lds, int wid, int lane) const {
;     ...
;             const float* slot = xbuf + (size_t)(u.pm * 256 + row) * 8; float t = 0.f;
; #pragma unroll
;             for (int k = 0; k < 8; ++k) t += __hip_atomic_load(slot + k, __ATOMIC_RELAXED, __HIP_MEMORY_SCOPE_AGENT);
; __device__ __forceinline__ void tr_all(const float* const* in, unsigned char* ws, LAS float* scr, int gw, int ngw, int lane, const TrRanges rg) {
;     ...
;         const LAS float* rp = scr + (8 * (lane & 7)) * 65 + (lane >> 3);
; #pragma unroll
;         for (int j = 0; j < 8; ++j) { const LAS float* s = rp + 8 * j;
;             u32x4 o; o.x = cvtpk(s[0 * 65] * g0[0], s[1 * 65] * g0[1]); o.y = cvtpk(s[2 * 65] * g0[2], s[3 * 65] * g0[3]);
;             o.z = cvtpk(s[4 * 65] * g1[0], s[5 * 65] * g1[1]); o.w = cvtpk(s[6 * 65] * g1[2], s[7 * 65] * g1[3]);
;             if (cur.nts) __builtin_nontemporal_store(o, (u32x4*)(cur.dst + (size_t)(8 * j) * cur.K)); else *(u32x4*)(cur.dst + (size_t)(8 * j) * cur.K) = o; }
;         asm volatile("s_waitcnt lgkmcnt(0)" ::: "memory");
	ds_write_b32 v70, v62 offset:15600
	ds_write_b32 v70, v63 offset:15604
	ds_write_b32 v70, v64 offset:15608
	ds_write_b32 v70, v65 offset:15612
	s_add_u32 s100, s84, 0x8f00000
	s_addc_u32 s101, s85, 0
	s_waitcnt vmcnt(0) lgkmcnt(0)
	ds_read_b32 v2, v71
	ds_read_b32 v3, v71 offset:260
	ds_read_b32 v4, v71 offset:520
	ds_read_b32 v5, v71 offset:780
	ds_read_b32 v6, v71 offset:1040
	ds_read_b32 v7, v71 offset:1300
	ds_read_b32 v8, v71 offset:1560
	ds_read_b32 v9, v71 offset:1820
	ds_read_b32 v10, v71 offset:32
	ds_read_b32 v11, v71 offset:292
	ds_read_b32 v12, v71 offset:552
	ds_read_b32 v13, v71 offset:812
	ds_read_b32 v14, v71 offset:1072
	ds_read_b32 v15, v71 offset:1332
	ds_read_b32 v16, v71 offset:1592
	ds_read_b32 v17, v71 offset:1852
	ds_read_b32 v18, v71 offset:64
	ds_read_b32 v19, v71 offset:324
	ds_read_b32 v20, v71 offset:584
	ds_read_b32 v21, v71 offset:844
	ds_read_b32 v22, v71 offset:1104
	ds_read_b32 v23, v71 offset:1364
	ds_read_b32 v24, v71 offset:1624
	ds_read_b32 v25, v71 offset:1884
	ds_read_b32 v26, v71 offset:96
	ds_read_b32 v27, v71 offset:356
	ds_read_b32 v28, v71 offset:616
	ds_read_b32 v29, v71 offset:876
	ds_read_b32 v30, v71 offset:1136
	ds_read_b32 v31, v71 offset:1396
	ds_read_b32 v32, v71 offset:1656
	ds_read_b32 v33, v71 offset:1916
	ds_read_b32 v34, v71 offset:128
	ds_read_b32 v35, v71 offset:388
	ds_read_b32 v36, v71 offset:648
	ds_read_b32 v37, v71 offset:908
	ds_read_b32 v38, v71 offset:1168
	ds_read_b32 v39, v71 offset:1428
	ds_read_b32 v40, v71 offset:1688
	ds_read_b32 v41, v71 offset:1948
	ds_read_b32 v42, v71 offset:160
	ds_read_b32 v43, v71 offset:420
	ds_read_b32 v44, v71 offset:680
	ds_read_b32 v45, v71 offset:940
	ds_read_b32 v46, v71 offset:1200
	ds_read_b32 v47, v71 offset:1460
	ds_read_b32 v48, v71 offset:1720
	ds_read_b32 v49, v71 offset:1980
	ds_read_b32 v50, v71 offset:192
	ds_read_b32 v51, v71 offset:452
	ds_read_b32 v52, v71 offset:712
	ds_read_b32 v53, v71 offset:972
	ds_read_b32 v54, v71 offset:1232
	ds_read_b32 v55, v71 offset:1492
	ds_read_b32 v56, v71 offset:1752
	ds_read_b32 v57, v71 offset:2012
	ds_read_b32 v58, v71 offset:224
	ds_read_b32 v59, v71 offset:484
	ds_read_b32 v60, v71 offset:744
	ds_read_b32 v61, v71 offset:1004
	ds_read_b32 v62, v71 offset:1264
	ds_read_b32 v63, v71 offset:1524
	ds_read_b32 v64, v71 offset:1784
	ds_read_b32 v65, v71 offset:2044
	s_waitcnt lgkmcnt(15)
	v_mul_f32_e32 v2, v2, v74
	v_mul_f32_e32 v3, v3, v75
	v_mul_f32_e32 v4, v4, v76
	v_mul_f32_e32 v5, v5, v77
	v_mul_f32_e32 v6, v6, v78
	v_mul_f32_e32 v7, v7, v79
	v_mul_f32_e32 v8, v8, v80
	v_mul_f32_e32 v9, v9, v81
	v_cvt_pk_bf16_f32 v192, v2, v3
	v_cvt_pk_bf16_f32 v193, v4, v5
	v_cvt_pk_bf16_f32 v194, v6, v7
	v_cvt_pk_bf16_f32 v195, v8, v9
	global_store_dwordx4 v72, v[192:195], s[100:101] nt
	s_waitcnt lgkmcnt(15)
	v_mul_f32_e32 v10, v10, v74
	v_mul_f32_e32 v11, v11, v75
	v_mul_f32_e32 v12, v12, v76
	v_mul_f32_e32 v13, v13, v77
	v_mul_f32_e32 v14, v14, v78
	v_mul_f32_e32 v15, v15, v79
	v_mul_f32_e32 v16, v16, v80
	v_mul_f32_e32 v17, v17, v81
	v_cvt_pk_bf16_f32 v196, v10, v11
	v_cvt_pk_bf16_f32 v197, v12, v13
	v_cvt_pk_bf16_f32 v198, v14, v15
	v_cvt_pk_bf16_f32 v199, v16, v17
	v_add_u32_e32 v68, 0x8000, v72
	global_store_dwordx4 v68, v[196:199], s[100:101] nt
	s_waitcnt lgkmcnt(15)
	v_mul_f32_e32 v18, v18, v74
	v_mul_f32_e32 v19, v19, v75
	v_mul_f32_e32 v20, v20, v76
	v_mul_f32_e32 v21, v21, v77
	v_mul_f32_e32 v22, v22, v78
	v_mul_f32_e32 v23, v23, v79
	v_mul_f32_e32 v24, v24, v80
	v_mul_f32_e32 v25, v25, v81
	v_cvt_pk_bf16_f32 v200, v18, v19
	v_cvt_pk_bf16_f32 v201, v20, v21
	v_cvt_pk_bf16_f32 v202, v22, v23
	v_cvt_pk_bf16_f32 v203, v24, v25
	v_add_u32_e32 v67, 0x10000, v72
	global_store_dwordx4 v67, v[200:203], s[100:101] nt
	s_waitcnt lgkmcnt(15)
	v_mul_f32_e32 v26, v26, v74
	v_mul_f32_e32 v27, v27, v75
	v_mul_f32_e32 v28, v28, v76
	v_mul_f32_e32 v29, v29, v77
	v_mul_f32_e32 v30, v30, v78
	v_mul_f32_e32 v31, v31, v79
	v_mul_f32_e32 v32, v32, v80
	v_mul_f32_e32 v33, v33, v81
	v_cvt_pk_bf16_f32 v204, v26, v27
	v_cvt_pk_bf16_f32 v205, v28, v29
	v_cvt_pk_bf16_f32 v206, v30, v31
	v_cvt_pk_bf16_f32 v207, v32, v33
	v_add_u32_e32 v68, 0x18000, v72
	global_store_dwordx4 v68, v[204:207], s[100:101] nt
	s_waitcnt lgkmcnt(15)
	v_mul_f32_e32 v34, v34, v74
	v_mul_f32_e32 v35, v35, v75
	v_mul_f32_e32 v36, v36, v76
	v_mul_f32_e32 v37, v37, v77
	v_mul_f32_e32 v38, v38, v78
	v_mul_f32_e32 v39, v39, v79
	v_mul_f32_e32 v40, v40, v80
	v_mul_f32_e32 v41, v41, v81
	v_cvt_pk_bf16_f32 v208, v34, v35
	v_cvt_pk_bf16_f32 v209, v36, v37
	v_cvt_pk_bf16_f32 v210, v38, v39
	v_cvt_pk_bf16_f32 v211, v40, v41
	v_add_u32_e32 v67, 0x20000, v72
	global_store_dwordx4 v67, v[208:211], s[100:101] nt
	s_waitcnt lgkmcnt(15)
	v_mul_f32_e32 v42, v42, v74
	v_mul_f32_e32 v43, v43, v75
	v_mul_f32_e32 v44, v44, v76
	v_mul_f32_e32 v45, v45, v77
	v_mul_f32_e32 v46, v46, v78
	v_mul_f32_e32 v47, v47, v79
	v_mul_f32_e32 v48, v48, v80
	v_mul_f32_e32 v49, v49, v81
	v_cvt_pk_bf16_f32 v212, v42, v43
	v_cvt_pk_bf16_f32 v213, v44, v45
	v_cvt_pk_bf16_f32 v214, v46, v47
	v_cvt_pk_bf16_f32 v215, v48, v49
	v_add_u32_e32 v68, 0x28000, v72
	global_store_dwordx4 v68, v[212:215], s[100:101] nt
	s_waitcnt lgkmcnt(8)
	v_mul_f32_e32 v50, v50, v74
	v_mul_f32_e32 v51, v51, v75
	v_mul_f32_e32 v52, v52, v76
	v_mul_f32_e32 v53, v53, v77
	v_mul_f32_e32 v54, v54, v78
	v_mul_f32_e32 v55, v55, v79
	v_mul_f32_e32 v56, v56, v80
	v_mul_f32_e32 v57, v57, v81
	v_cvt_pk_bf16_f32 v216, v50, v51
	v_cvt_pk_bf16_f32 v217, v52, v53
	v_cvt_pk_bf16_f32 v218, v54, v55
	v_cvt_pk_bf16_f32 v219, v56, v57
	v_add_u32_e32 v67, 0x30000, v72
	global_store_dwordx4 v67, v[216:219], s[100:101] nt
	s_waitcnt lgkmcnt(0)
	v_mul_f32_e32 v58, v58, v74
	v_mul_f32_e32 v59, v59, v75
	v_mul_f32_e32 v60, v60, v76
	v_mul_f32_e32 v61, v61, v77
	v_mul_f32_e32 v62, v62, v78
	v_mul_f32_e32 v63, v63, v79
	v_mul_f32_e32 v64, v64, v80
	v_mul_f32_e32 v65, v65, v81
	v_cvt_pk_bf16_f32 v220, v58, v59
	v_cvt_pk_bf16_f32 v221, v60, v61
	v_cvt_pk_bf16_f32 v222, v62, v63
	v_cvt_pk_bf16_f32 v223, v64, v65
	v_add_u32_e32 v68, 0x38000, v72
	global_store_dwordx4 v68, v[220:223], s[100:101] nt
	s_branch .LBB0_681
.Lseam_cv_2_1:
	s_cmp_gt_u32 s98, 6
	s_cbranch_scc1 .LBB0_681
	s_mov_b64 exec, -1
	v_and_b32_e32 v66, 63, v1
	s_lshl_b32 s99, s87, 10
	v_lshlrev_b32_e32 v66, 4, v66
	v_add_u32_e32 v66, s99, v66
	s_add_u32 s100, s84, 0x80000
	s_addc_u32 s101, s85, 0
	v_mov_b32_e32 v2, 0xbf800000
	v_mov_b32_e32 v3, 0xbf800000
	v_mov_b32_e32 v4, 0xbf800000
	v_mov_b32_e32 v5, 0xbf800000
	global_store_dwordx4 v66, v[2:5], s[100:101] sc1

;     __device__ __forceinline__ void fused(f32x4 (&acc)[2][2][4][2], const Unit& u, int wr, int wc, int fr, int fq, PG8_LAS unsigned char* lds, int wid, int lane) const {
;     ...
;         asm volatile("s_waitcnt lgkmcnt(0)" ::: "memory"); __builtin_amdgcn_s_barrier(); asm volatile("" ::: "memory");
;         const int row = wid * 32 + (lane & 31);
;         if (lane < 32) {
;             const float t = (P[row * 4 + 0] + P[row * 4 + 1]) + (P[row * 4 + 2] + P[row * 4 + 3]);
;             __hip_atomic_store(xbuf + (size_t)(u.pm * 256 + row) * 8 + u.pn, t, __ATOMIC_RELAXED, __HIP_MEMORY_SCOPE_AGENT);
;         }
;         asm volatile("s_waitcnt vmcnt(0)" ::: "memory");
;         unsigned* c = cnt + 64 * u.pm;
;         if (lane == 0) __hip_atomic_fetch_add(c, 1u, __ATOMIC_RELAXED, __HIP_MEMORY_SCOPE_AGENT);
;         if (wid == 0) {
;             unsigned sp = 0;
;             while ((unsigned)__builtin_amdgcn_readfirstlane(__hip_atomic_load(c, __ATOMIC_RELAXED, __HIP_MEMORY_SCOPE_AGENT)) < 64u) { __builtin_amdgcn_s_sleep(2); if (++sp > (1u << 22)) break; }
;             __builtin_amdgcn_fence(__ATOMIC_ACQUIRE, "agent");
;         }
;         asm volatile("s_waitcnt vmcnt(0) lgkmcnt(0)" ::: "memory"); __builtin_amdgcn_s_barrier(); asm volatile("" ::: "memory");
;         if (lane < 32) {
;             const float* slot = xbuf + (size_t)(u.pm * 256 + row) * 8; float t = 0.f;
; #pragma unroll
;             for (int k = 0; k < 8; ++k) t += __hip_atomic_load(slot + k, __ATOMIC_RELAXED, __HIP_MEMORY_SCOPE_AGENT);
;             S[row] = rsqrtf(t * (1.0f / D) + EPS);
;         }
;         asm volatile("s_waitcnt vmcnt(0) lgkmcnt(0)" ::: "memory"); __builtin_amdgcn_s_barrier(); asm volatile("" ::: "memory");
;         f32x4 g[2][2];
; #pragma unroll
;         for (int bj = 0; bj < 2; ++bj) { g[bj][0] = *(const f32x4*)(gain + col0 + bj * 128); g[bj][1] = *(const f32x4*)(gain + col0 + bj * 128 + 4); }
.LBB0_1929:
	s_or_b64 exec, exec, s[4:5]
	v_readlane_b32 s98, v254, 0
	v_readlane_b32 s99, v254, 1
	s_nop 3
	v_lshl_add_u64 v[252:253], v[132:133], 2, s[98:99]
	global_load_dwordx4 v[236:239], v[252:253], off
	global_load_dwordx4 v[240:243], v[252:253], off offset:16
	global_load_dwordx4 v[244:247], v[252:253], off offset:512
	global_load_dwordx4 v[248:251], v[252:253], off offset:528
	s_and_saveexec_b64 s[4:5], s[0:1]
	v_lshlrev_b64 v[2:3], 5, v[2:3]
	v_lshl_add_u64 v[2:3], s[2:3], 0, v[2:3]
	s_movk_i32 s12, 0x800
.Lfin_poll:
	global_load_dword v5, v[2:3], off sc1
	global_load_dword v6, v[2:3], off offset:4 sc1
	global_load_dword v7, v[2:3], off offset:8 sc1
	global_load_dword v8, v[2:3], off offset:12 sc1
	global_load_dword v9, v[2:3], off offset:16 sc1
	global_load_dword v10, v[2:3], off offset:20 sc1
	global_load_dword v11, v[2:3], off offset:24 sc1
	global_load_dword v12, v[2:3], off offset:28 sc1
	s_waitcnt vmcnt(0)
	v_or3_b32 v13, v5, v6, v7
	v_or3_b32 v13, v13, v8, v9
	v_or3_b32 v13, v13, v10, v11
	v_or_b32_e32 v13, v13, v12
	v_cmp_gt_i32_e32 vcc, 0, v13
	s_cbranch_vccz .Lfin_done
	s_add_i32 s12, s12, -1
	s_cmp_eq_u32 s12, 0
	s_cbranch_scc1 .Lfin_done
	s_sleep 2
	s_branch .Lfin_poll
.Lfin_done:
	v_mov_b32_e32 v3, 0x358637bd
	s_mov_b32 s0, 0x800000
	v_add_f32_e32 v5, 0, v5
	v_add_f32_e32 v5, v5, v6
	v_add_f32_e32 v5, v5, v7
	v_add_f32_e32 v5, v5, v8
	v_add_f32_e32 v5, v5, v9
	v_add_f32_e32 v5, v5, v10
	v_add_f32_e32 v5, v5, v11
	v_add_f32_e32 v2, v5, v12
	v_fmac_f32_e32 v3, 0x3a000000, v2
	v_mul_f32_e32 v2, 0x4b800000, v3
	v_cmp_gt_f32_e32 vcc, s0, v3
	s_nop 1
	v_cndmask_b32_e32 v2, v3, v2, vcc
	v_rsq_f32_e32 v2, v2
	s_nop 0
	v_mul_f32_e32 v3, 0x45800000, v2
	v_cndmask_b32_e32 v2, v2, v3, vcc
	v_lshl_add_u32 v3, v4, 2, 0
	ds_write_b32 v3, v2 offset:4096
.LBB0_1944:
	s_or_b64 exec, exec, s[4:5]
	v_readlane_b32 s0, v254, 0
	v_lshlrev_b64 v[132:133], 2, v[132:133]
	v_readlane_b32 s1, v254, 1
	s_waitcnt vmcnt(0) lgkmcnt(0)
	s_barrier
	v_readlane_b32 s2, v254, 2
	v_lshl_add_u64 v[2:3], s[0:1], 0, v[132:133]
	v_mov_b64_e32 v[14:15], v[236:237]
	v_mov_b64_e32 v[16:17], v[238:239]
	v_mov_b64_e32 v[10:11], v[240:241]
	v_mov_b64_e32 v[12:13], v[242:243]
	v_mov_b64_e32 v[6:7], v[244:245]
	v_mov_b64_e32 v[8:9], v[246:247]
	s_nop 0
	v_mov_b64_e32 v[2:3], v[248:249]
	v_mov_b64_e32 v[4:5], v[250:251]
	v_readlane_b32 s3, v254, 3
	v_lshl_add_u32 v164, v164, 2, 0
	v_lshlrev_b64 v[130:131], 13, v[130:131]
	v_add_u32_e32 v183, 0x1000, v164
	v_lshl_add_u64 v[130:131], s[2:3], 0, v[130:131]
	ds_read2_b32 v[164:165], v183 offset1:16
	v_lshl_add_u64 v[166:167], v[130:131], 0, v[132:133]
	ds_read2_b32 v[130:131], v183 offset0:32 offset1:48
	v_lshlrev_b64 v[134:135], 13, v[134:135]
	v_lshlrev_b64 v[136:137], 13, v[136:137]
	s_waitcnt lgkmcnt(1)
	v_pk_mul_f32 v[126:127], v[126:127], v[164:165] op_sel_hi:[1,0]
	v_pk_mul_f32 v[128:129], v[128:129], v[164:165] op_sel_hi:[1,0]
	v_pk_mul_f32 v[122:123], v[122:123], v[164:165] op_sel_hi:[1,0]
	v_pk_mul_f32 v[124:125], v[124:125], v[164:165] op_sel_hi:[1,0]
	v_pk_mul_f32 v[118:119], v[118:119], v[164:165] op_sel_hi:[1,0]
	v_pk_mul_f32 v[120:121], v[120:121], v[164:165] op_sel_hi:[1,0]
	v_pk_mul_f32 v[114:115], v[114:115], v[164:165] op_sel_hi:[1,0]
	v_pk_mul_f32 v[116:117], v[116:117], v[164:165] op_sel_hi:[1,0]
	v_mov_b32_e32 v164, v165
	s_waitcnt lgkmcnt(0)
	v_mov_b32_e32 v182, v131
	v_lshlrev_b64 v[82:83], 13, v[82:83]
	v_lshl_add_u64 v[134:135], s[2:3], 0, v[134:135]
	v_lshl_add_u64 v[136:137], s[2:3], 0, v[136:137]
	v_pk_mul_f32 v[138:139], v[138:139], v[130:131] op_sel_hi:[1,0]
	v_pk_mul_f32 v[168:169], v[96:97], v[130:131] op_sel_hi:[1,0]
	v_pk_mul_f32 v[170:171], v[94:95], v[130:131] op_sel_hi:[1,0]
	v_pk_mul_f32 v[172:173], v[92:93], v[130:131] op_sel_hi:[1,0]
	v_pk_mul_f32 v[174:175], v[90:91], v[130:131] op_sel_hi:[1,0]
	v_pk_mul_f32 v[176:177], v[88:89], v[130:131] op_sel_hi:[1,0]
	v_pk_mul_f32 v[178:179], v[86:87], v[130:131] op_sel_hi:[1,0]
	v_pk_mul_f32 v[180:181], v[84:85], v[130:131] op_sel_hi:[1,0]
	v_pk_mul_f32 v[110:111], v[110:111], v[164:165] op_sel_hi:[1,0]
	v_pk_mul_f32 v[112:113], v[112:113], v[164:165] op_sel_hi:[1,0]
	v_pk_mul_f32 v[130:131], v[106:107], v[164:165] op_sel_hi:[1,0]
	v_pk_mul_f32 v[106:107], v[108:109], v[164:165] op_sel_hi:[1,0]
	v_pk_mul_f32 v[108:109], v[102:103], v[164:165] op_sel_hi:[1,0]
	v_pk_mul_f32 v[184:185], v[104:105], v[164:165] op_sel_hi:[1,0]
	v_pk_mul_f32 v[186:187], v[98:99], v[164:165] op_sel_hi:[1,0]
	v_pk_mul_f32 v[164:165], v[100:101], v[164:165] op_sel_hi:[1,0]
	v_lshl_add_u64 v[82:83], s[2:3], 0, v[82:83]
	v_pk_mul_f32 v[70:71], v[70:71], v[182:183] op_sel_hi:[1,0]
	v_pk_mul_f32 v[72:73], v[72:73], v[182:183] op_sel_hi:[1,0]
	v_lshl_add_u64 v[134:135], v[134:135], 0, v[132:133]
	v_lshl_add_u64 v[136:137], v[136:137], 0, v[132:133]
	v_lshl_add_u64 v[82:83], v[82:83], 0, v[132:133]
	v_pk_mul_f32 v[66:67], v[66:67], v[182:183] op_sel_hi:[1,0]
	v_pk_mul_f32 v[68:69], v[68:69], v[182:183] op_sel_hi:[1,0]
	v_pk_mul_f32 v[78:79], v[78:79], v[182:183] op_sel_hi:[1,0]
	v_pk_mul_f32 v[80:81], v[80:81], v[182:183] op_sel_hi:[1,0]
	v_pk_mul_f32 v[74:75], v[74:75], v[182:183] op_sel_hi:[1,0]
	v_pk_mul_f32 v[76:77], v[76:77], v[182:183] op_sel_hi:[1,0]
	s_waitcnt vmcnt(3)
	v_pk_mul_f32 v[86:87], v[16:17], v[128:129]
	v_pk_mul_f32 v[84:85], v[14:15], v[126:127]
	s_waitcnt vmcnt(2)
	v_pk_mul_f32 v[90:91], v[12:13], v[124:125]
	v_pk_mul_f32 v[88:89], v[10:11], v[122:123]
	s_waitcnt vmcnt(1)
	v_pk_mul_f32 v[94:95], v[8:9], v[120:121]
	v_pk_mul_f32 v[92:93], v[6:7], v[118:119]
	s_waitcnt vmcnt(0)
;     __device__ __forceinline__ void fused(f32x4 (&acc)[2][2][4][2], const Unit& u, int wr, int wc, int fr, int fq, PG8_LAS unsigned char* lds, int wid, int lane) const {
;     ...
; #pragma unroll
;         for (int ai = 0; ai < 2; ++ai)
; #pragma unroll
;             for (int m = 0; m < 4; ++m) {
;                 const int rl = ai * 128 + wr * 64 + m * 16 + fr; const float rs = S[rl];
; #pragma unroll
;                 for (int bj = 0; bj < 2; ++bj) {
;                     const size_t off = (size_t)(u.pm * 256 + rl) * D + col0 + bj * 128;
;                     *(f32x4*)(out + off) = acc[ai][bj][m][0] * rs * g[bj][0]; *(f32x4*)(out + off + 4) = acc[ai][bj][m][1] * rs * g[bj][1];
;                 }
;             }
	v_pk_mul_f32 v[98:99], v[4:5], v[116:117]
	v_pk_mul_f32 v[96:97], v[2:3], v[114:115]
	v_pk_mul_f32 v[102:103], v[16:17], v[112:113]
	v_pk_mul_f32 v[100:101], v[14:15], v[110:111]
	v_pk_mul_f32 v[106:107], v[12:13], v[106:107]
	v_pk_mul_f32 v[104:105], v[10:11], v[130:131]
	v_pk_mul_f32 v[110:111], v[8:9], v[184:185]
	v_pk_mul_f32 v[108:109], v[6:7], v[108:109]
	v_pk_mul_f32 v[114:115], v[4:5], v[164:165]
	v_pk_mul_f32 v[112:113], v[2:3], v[186:187]
	v_pk_mul_f32 v[118:119], v[16:17], v[168:169]
	v_pk_mul_f32 v[116:117], v[14:15], v[138:139]
	v_pk_mul_f32 v[122:123], v[12:13], v[172:173]
	v_pk_mul_f32 v[120:121], v[10:11], v[170:171]
	v_pk_mul_f32 v[126:127], v[8:9], v[176:177]
	v_pk_mul_f32 v[124:125], v[6:7], v[174:175]
	v_pk_mul_f32 v[130:131], v[4:5], v[180:181]
	v_pk_mul_f32 v[128:129], v[2:3], v[178:179]
	global_store_dwordx4 v[166:167], v[84:87], off
	global_store_dwordx4 v[166:167], v[88:91], off offset:16
	global_store_dwordx4 v[166:167], v[92:95], off offset:512
	global_store_dwordx4 v[166:167], v[96:99], off offset:528
	global_store_dwordx4 v[134:135], v[100:103], off
	global_store_dwordx4 v[134:135], v[104:107], off offset:16
	global_store_dwordx4 v[134:135], v[108:111], off offset:512
	global_store_dwordx4 v[134:135], v[112:115], off offset:528
	global_store_dwordx4 v[136:137], v[116:119], off
	global_store_dwordx4 v[136:137], v[120:123], off offset:16
	global_store_dwordx4 v[136:137], v[124:127], off offset:512
	global_store_dwordx4 v[136:137], v[128:131], off offset:528
	v_pk_mul_f32 v[72:73], v[8:9], v[72:73]
	v_pk_mul_f32 v[70:71], v[6:7], v[70:71]
	global_store_dwordx4 v[82:83], v[70:73], off offset:512
	ds_read2_b32 v[70:71], v183 offset0:128 offset1:144
	v_pk_mul_f32 v[68:69], v[4:5], v[68:69]
	v_pk_mul_f32 v[66:67], v[2:3], v[66:67]
	global_store_dwordx4 v[82:83], v[66:69], off offset:528
	v_pk_mul_f32 v[78:79], v[14:15], v[78:79]
	s_waitcnt lgkmcnt(0)
	v_pk_mul_f32 v[50:51], v[50:51], v[70:71] op_sel_hi:[1,0]
	v_lshlrev_b64 v[66:67], 13, v[140:141]
	v_lshl_add_u64 v[66:67], s[2:3], 0, v[66:67]
	v_pk_mul_f32 v[52:53], v[52:53], v[70:71] op_sel_hi:[1,0]
	v_lshl_add_u64 v[66:67], v[66:67], 0, v[132:133]
	v_pk_mul_f32 v[52:53], v[4:5], v[52:53]
	v_pk_mul_f32 v[50:51], v[2:3], v[50:51]
	global_store_dwordx4 v[66:67], v[50:53], off offset:528
	v_pk_mul_f32 v[62:63], v[62:63], v[70:71] op_sel_hi:[1,0]
	v_pk_mul_f32 v[64:65], v[64:65], v[70:71] op_sel_hi:[1,0]
	v_mov_b32_e32 v50, v71
	v_lshlrev_b64 v[52:53], 13, v[142:143]
	v_lshl_add_u64 v[52:53], s[2:3], 0, v[52:53]
	v_pk_mul_f32 v[38:39], v[38:39], v[50:51] op_sel_hi:[1,0]
	v_pk_mul_f32 v[40:41], v[40:41], v[50:51] op_sel_hi:[1,0]
	v_lshl_add_u64 v[52:53], v[52:53], 0, v[132:133]
	v_pk_mul_f32 v[40:41], v[8:9], v[40:41]
	v_pk_mul_f32 v[38:39], v[6:7], v[38:39]
	global_store_dwordx4 v[52:53], v[38:41], off offset:512
	ds_read2_b32 v[38:39], v183 offset0:160 offset1:176
	v_pk_mul_f32 v[34:35], v[34:35], v[50:51] op_sel_hi:[1,0]
	v_pk_mul_f32 v[36:37], v[36:37], v[50:51] op_sel_hi:[1,0]
	v_pk_mul_f32 v[34:35], v[2:3], v[34:35]
	v_pk_mul_f32 v[36:37], v[4:5], v[36:37]
	global_store_dwordx4 v[52:53], v[34:37], off offset:528
	s_waitcnt lgkmcnt(0)
	v_pk_mul_f32 v[18:19], v[18:19], v[38:39] op_sel_hi:[1,0]
	v_pk_mul_f32 v[20:21], v[20:21], v[38:39] op_sel_hi:[1,0]
	v_lshlrev_b64 v[34:35], 13, v[144:145]
	v_lshl_add_u64 v[34:35], s[2:3], 0, v[34:35]
	v_lshl_add_u64 v[34:35], v[34:35], 0, v[132:133]
	v_pk_mul_f32 v[20:21], v[4:5], v[20:21]
	v_pk_mul_f32 v[18:19], v[2:3], v[18:19]
	global_store_dwordx4 v[34:35], v[18:21], off offset:528
	v_pk_mul_f32 v[46:47], v[46:47], v[50:51] op_sel_hi:[1,0]
	v_pk_mul_f32 v[30:31], v[30:31], v[38:39] op_sel_hi:[1,0]
	v_mov_b32_e32 v18, v39
	v_pk_mul_f32 v[22:23], v[22:23], v[38:39] op_sel_hi:[1,0]
	v_pk_mul_f32 v[24:25], v[24:25], v[38:39] op_sel_hi:[1,0]
	v_pk_mul_f32 v[20:21], v[162:163], v[18:19] op_sel_hi:[1,0]
	v_pk_mul_f32 v[62:63], v[14:15], v[62:63]
	v_pk_mul_f32 v[46:47], v[14:15], v[46:47]
	v_pk_mul_f32 v[30:31], v[14:15], v[30:31]
	v_pk_mul_f32 v[24:25], v[8:9], v[24:25]
	v_pk_mul_f32 v[22:23], v[6:7], v[22:23]
	v_pk_mul_f32 v[14:15], v[14:15], v[20:21]
	v_lshlrev_b64 v[20:21], 13, v[146:147]
	v_pk_mul_f32 v[48:49], v[48:49], v[50:51] op_sel_hi:[1,0]
	v_pk_mul_f32 v[32:33], v[32:33], v[38:39] op_sel_hi:[1,0]
	global_store_dwordx4 v[34:35], v[22:25], off offset:512
	v_lshl_add_u64 v[20:21], s[2:3], 0, v[20:21]
	v_pk_mul_f32 v[80:81], v[16:17], v[80:81]
	v_pk_mul_f32 v[22:23], v[160:161], v[18:19] op_sel_hi:[1,0]
	v_pk_mul_f32 v[64:65], v[16:17], v[64:65]
	v_pk_mul_f32 v[48:49], v[16:17], v[48:49]
	v_pk_mul_f32 v[32:33], v[16:17], v[32:33]
	v_pk_mul_f32 v[16:17], v[16:17], v[22:23]
	v_lshl_add_u64 v[20:21], v[20:21], 0, v[132:133]
	global_store_dwordx4 v[82:83], v[78:81], off
	v_pk_mul_f32 v[58:59], v[58:59], v[70:71] op_sel_hi:[1,0]
	v_pk_mul_f32 v[60:61], v[60:61], v[70:71] op_sel_hi:[1,0]
	v_pk_mul_f32 v[42:43], v[42:43], v[50:51] op_sel_hi:[1,0]
	v_pk_mul_f32 v[44:45], v[44:45], v[50:51] op_sel_hi:[1,0]
	v_pk_mul_f32 v[26:27], v[26:27], v[38:39] op_sel_hi:[1,0]
	v_pk_mul_f32 v[28:29], v[28:29], v[38:39] op_sel_hi:[1,0]
	global_store_dwordx4 v[20:21], v[14:17], off
	v_pk_mul_f32 v[76:77], v[12:13], v[76:77]
	v_pk_mul_f32 v[74:75], v[10:11], v[74:75]
	v_pk_mul_f32 v[14:15], v[158:159], v[18:19] op_sel_hi:[1,0]
	v_pk_mul_f32 v[16:17], v[154:155], v[18:19] op_sel_hi:[1,0]
	v_pk_mul_f32 v[60:61], v[12:13], v[60:61]
	v_pk_mul_f32 v[58:59], v[10:11], v[58:59]
	v_pk_mul_f32 v[44:45], v[12:13], v[44:45]
	v_pk_mul_f32 v[42:43], v[10:11], v[42:43]
	v_pk_mul_f32 v[28:29], v[12:13], v[28:29]
	v_pk_mul_f32 v[26:27], v[10:11], v[26:27]
	v_pk_mul_f32 v[12:13], v[12:13], v[16:17]
	v_pk_mul_f32 v[10:11], v[10:11], v[14:15]
	global_store_dwordx4 v[82:83], v[74:77], off offset:16
	v_pk_mul_f32 v[54:55], v[54:55], v[70:71] op_sel_hi:[1,0]
	v_pk_mul_f32 v[56:57], v[56:57], v[70:71] op_sel_hi:[1,0]
	global_store_dwordx4 v[20:21], v[10:13], off offset:16
	v_pk_mul_f32 v[56:57], v[8:9], v[56:57]
	v_pk_mul_f32 v[54:55], v[6:7], v[54:55]
	v_pk_mul_f32 v[10:11], v[156:157], v[18:19] op_sel_hi:[1,0]
	v_pk_mul_f32 v[12:13], v[150:151], v[18:19] op_sel_hi:[1,0]
	v_pk_mul_f32 v[6:7], v[6:7], v[10:11]
	v_pk_mul_f32 v[8:9], v[8:9], v[12:13]
	global_store_dwordx4 v[20:21], v[6:9], off offset:512
	global_store_dwordx4 v[66:67], v[62:65], off
	global_store_dwordx4 v[66:67], v[58:61], off offset:16
	v_pk_mul_f32 v[6:7], v[152:153], v[18:19] op_sel_hi:[1,0]
	v_pk_mul_f32 v[8:9], v[148:149], v[18:19] op_sel_hi:[1,0]
	v_pk_mul_f32 v[2:3], v[2:3], v[6:7]
	v_pk_mul_f32 v[4:5], v[4:5], v[8:9]
	global_store_dwordx4 v[66:67], v[54:57], off offset:512
	global_store_dwordx4 v[52:53], v[46:49], off
	global_store_dwordx4 v[52:53], v[42:45], off offset:16
	global_store_dwordx4 v[34:35], v[30:33], off
	global_store_dwordx4 v[34:35], v[26:29], off offset:16
	global_store_dwordx4 v[20:21], v[2:5], off offset:528
